# GEMM1: no store-drain wait before the mode-2 trailing barrier nor at tile start (counted waits cover older stores in order)
# speedup vs baseline: 1.0091x; 1.0091x over previous
.LBB0_197:
	s_load_dwordx2 s[20:21], s[20:21], 0x0
	s_nop 0
	s_load_dwordx2 s[36:37], s[26:27], 0x0
	s_load_dwordx2 vcc, s[24:25], 0x0
	s_lshl_b32 s24, s38, 8
	s_lshl_b32 s26, s88, 8
	v_readfirstlane_b32 s89, v0
	s_lshr_b32 s72, s89, 6
	s_ashr_i32 s25, s24, 31
	s_ashr_i32 s27, s26, 31
	s_lshr_b32 s45, s89, 8
	s_lshl_b32 s82, s72, 10
	s_lshl_b64 s[38:39], s[24:25], 11
	s_lshl_b64 s[86:87], s[26:27], 11
	s_waitcnt lgkmcnt(0)
	s_add_u32 s56, vcc_lo, s86
	s_addc_u32 s57, vcc_hi, s87
	s_add_i32 s27, s82, 16
	s_add_i32 m0, s27, 0x10000
	v_lshl_add_u64 v[2:3], s[56:57], 0, v[140:141]
	global_load_lds_dwordx4 v[2:3], off
	s_add_i32 m0, s27, 0x12000
	s_add_u32 s40, s36, s38
	v_lshl_add_u64 v[4:5], s[56:57], 0, v[144:145]
	s_addc_u32 s41, s37, s39
	s_add_i32 s84, s27, 0x2000
	global_load_lds_dwordx4 v[4:5], off
	v_lshl_add_u64 v[8:9], s[40:41], 0, v[138:139]
	s_mov_b32 m0, s27
	s_add_u32 s14, s56, 0x40000
	global_load_lds_dwordx4 v[8:9], off
	v_lshl_add_u64 v[6:7], s[40:41], 0, v[142:143]
	s_mov_b32 m0, s84
	s_addc_u32 s15, s57, 0
	global_load_lds_dwordx4 v[6:7], off
	s_add_i32 m0, s27, 0x14000
	v_lshl_add_u64 v[10:11], s[14:15], 0, v[140:141]
	global_load_lds_dwordx4 v[10:11], off
	s_add_i32 m0, s27, 0x16000
	v_lshl_add_u64 v[10:11], s[14:15], 0, v[144:145]
	s_add_u32 s14, s40, 0x40000
	s_addc_u32 s15, s41, 0
	s_add_i32 s85, s27, 0x4000
	global_load_lds_dwordx4 v[10:11], off
	v_lshl_add_u64 v[10:11], s[14:15], 0, v[138:139]
	s_mov_b32 m0, s85
	s_add_i32 s44, s27, 0x6000
	global_load_lds_dwordx4 v[10:11], off
	v_lshl_add_u64 v[10:11], s[14:15], 0, v[142:143]
	s_mov_b32 m0, s44
	s_cmp_lg_u32 s45, 1
	global_load_lds_dwordx4 v[10:11], off
	s_cbranch_scc1 .LBB0_199
	s_barrier

.LBB0_302:
	v_cvt_pk_bf16_f32 v130, v130, v131
	v_cvt_pk_bf16_f32 v131, v132, v133
	v_cvt_pk_bf16_f32 v132, v134, v135
	v_cvt_pk_bf16_f32 v133, v136, v137
	s_and_b64 vcc, exec, s[40:41]
	global_store_dwordx4 v[160:161], v[130:133], off offset:256
	s_cbranch_vccnz .LBB0_304
	s_barrier
